# baseline (speedup 1.0000x reference)
; #define IDX_STAGE(c_) do { if ((c_) + 1 < nch) { *(u32x4*)(kt_l + (((c_) + 1) & 1) * 8192 + tid * 16) = st0; \
;           if ((c_) + 2 < nch) st0 = *(const u32x4*)(kbase + (size_t)(((c_) + 2) * 32 + j0) * 128 + cch); } } while (0)
; __device__ __forceinline__ void indexer_phase(const Params& P, char* lds) {
;     ...
;       const u16* kbase = P_kidx + (size_t)b * SEQ * 128;
;       const int j0 = tid >> 4, p0 = tid & 15;
;       const int cch = (p0 ^ (j0 & 15)) * 8;
;       u32x4 st0;
;       st0 = *(const u32x4*)(kbase + (size_t)(j0) * 128 + cch);
;       const int boff = r32 * 256;
;       __syncthreads();
;       *(u32x4*)(kt_l + tid * 16) = st0;
;       if (nch > 1) st0 = *(const u32x4*)(kbase + (size_t)(32 + j0) * 128 + cch);
;       __syncthreads();
;     ...
;       f32x16 xa0, xa1, ya0, ya1;
;       IDX_STAGE(0); IDX_MMA(xa0, xa1, 0);
;       __syncthreads();
;       for (int c = 1; c < nch; c += 2) {
.LBB0_466:
	v_add_u32_e32 v32, v188, v193
	ds_read_b128 v[48:51], v32
	v_add_u32_e32 v203, v188, v196
	ds_read_b128 v[204:207], v203
	v_add_u32_e32 v32, v188, v194
	ds_read_b128 v[180:183], v32
	s_waitcnt lgkmcnt(2)
	v_mfma_f32_32x32x16_bf16 v[32:47], v[96:99], v[48:51], 0
	v_add_u32_e32 v203, v188, v198
	s_and_b64 vcc, exec, s[8:9]
	v_mfma_f32_32x32x16_bf16 v[48:63], v[128:131], v[48:51], 0
	s_waitcnt lgkmcnt(0)
	v_mfma_f32_32x32x16_bf16 v[32:47], v[100:103], v[180:183], v[32:47]
	v_mfma_f32_32x32x16_bf16 v[48:63], v[132:135], v[180:183], v[48:63]
	v_add_u32_e32 v180, v188, v195
	ds_read_b128 v[180:183], v180
	s_waitcnt lgkmcnt(0)
	v_mfma_f32_32x32x16_bf16 v[32:47], v[104:107], v[180:183], v[32:47]
	v_mfma_f32_32x32x16_bf16 v[48:63], v[136:139], v[180:183], v[48:63]
	v_add_u32_e32 v180, v188, v197
	ds_read_b128 v[180:183], v180
	v_mfma_f32_32x32x16_bf16 v[32:47], v[108:111], v[204:207], v[32:47]
	v_mfma_f32_32x32x16_bf16 v[48:63], v[140:143], v[204:207], v[48:63]
	ds_read_b128 v[204:207], v203
	v_add_u32_e32 v203, v188, v200
	s_waitcnt lgkmcnt(1)
	v_mfma_f32_32x32x16_bf16 v[32:47], v[112:115], v[180:183], v[32:47]
	v_mfma_f32_32x32x16_bf16 v[48:63], v[144:147], v[180:183], v[48:63]
	v_add_u32_e32 v180, v188, v199
	ds_read_b128 v[180:183], v180
	s_waitcnt lgkmcnt(1)
	v_mfma_f32_32x32x16_bf16 v[32:47], v[116:119], v[204:207], v[32:47]
	v_mfma_f32_32x32x16_bf16 v[48:63], v[148:151], v[204:207], v[48:63]
	ds_read_b128 v[204:207], v203
	s_waitcnt lgkmcnt(0)
	s_barrier
	v_mfma_f32_32x32x16_bf16 v[32:47], v[120:123], v[180:183], v[32:47]
	v_mfma_f32_32x32x16_bf16 v[48:63], v[152:155], v[180:183], v[48:63]
	v_mfma_f32_32x32x16_bf16 v[32:47], v[124:127], v[204:207], v[32:47]
	v_mfma_f32_32x32x16_bf16 v[48:63], v[156:159], v[204:207], v[48:63]
	s_cbranch_vccnz .LBB0_482
	v_and_b32_e32 v1, 64, v202
	v_xor_b32_e32 v0, 32, v202
	v_add_u32_e32 v1, 64, v1
	v_cmp_lt_i32_e32 vcc, v0, v1
	v_lshl_add_u64 v[180:181], s[12:13], 0, v[168:169]
	s_add_i32 s12, s14, -2
	v_cndmask_b32_e32 v0, v202, v0, vcc
	v_lshlrev_b32_e32 v203, 2, v0
	s_mov_b32 s15, 4
	s_movk_i32 s13, 0x2000
	v_add_u32_e32 v244, 0x22010, v170
	v_add_u32_e32 v237, v244, v193
	v_add_u32_e32 v238, v244, v194
	v_add_u32_e32 v239, v244, v195
	v_add_u32_e32 v240, v244, v196
	v_add_u32_e32 v241, v244, v197
	v_add_u32_e32 v242, v244, v198
	v_add_u32_e32 v243, v244, v199
	v_add_u32_e32 v244, v244, v200
	v_add_u32_e32 v245, v188, v193
	v_add_u32_e32 v246, v188, v194
	v_add_u32_e32 v247, v188, v195
	v_add_u32_e32 v248, v188, v196
	v_add_u32_e32 v249, v188, v197
	v_add_u32_e32 v251, v188, v198
	v_add_u32_e32 v252, v188, v199
	v_add_u32_e32 v253, v188, v200
	v_mov_b32_e32 v204, v189
	v_mov_b32_e32 v182, v171
	.p2align	6

; __device__ __forceinline__ int v_rd_base(int lane) { return ((lane & 3) << 3) | (((lane >> 2) & 3) << 6) | (((lane >> 4) & 1) << 5) | (((lane >> 5) & 1) << 8); }
; template <int MODE>
; __device__ __forceinline__ void attn_item(const Params& P, int b, int h, int qb, char* lds) {
;   int tid = threadIdx.x; asm volatile("" : "+v"(tid));
;   const int lane = tid & 63, wid = __builtin_amdgcn_readfirstlane(tid >> 6), r32 = lane & 31, hi = lane >> 5;
;   char* V_lds = lds;
;   char* K_lds = lds + 32768;
;   float* cs_l = (float*)(lds + 65536);
;   float* ws = (float*)(lds + 65536 + 512) + wid * 64;
;   float* al_l = ws; float* li_l = ws + 32;
;   const u16 *Qp, *Kp, *Vp;
;   if (MODE == 0) {
;     Qp = P_qA + (size_t)(b * 32 + h) * SEQ * 128; Kp = P_kA + (size_t)(b * 4 + (h >> 3)) * SEQ * 128; Vp = P_vA + (size_t)(b * 4 + (h >> 3)) * SEQ * 128;
;   } else {
;     Qp = P_q1 + (size_t)(b * 32 + h) * SEQ * 128; Kp = P_k1 + (size_t)(b * 32 + h) * SEQ * 128; Vp = P_v1 + (size_t)(b * 32 + h) * SEQ * 128;
;   }
;   const int q0 = qb * 256 + wid * 32, qpos = q0 + r32;
;   const int NT = 4 * qb + 4;
;   bf16x8 qr[8];
; #pragma unroll
;   for (int d0 = 0; d0 < 8; ++d0) qr[d0] = *(const bf16x8*)(Qp + (size_t)qpos * 128 + d0 * 16 + hi * 8);
;   const float* c2p = P_c2 + (size_t)(b * 32 + h) * SEQ;
;   float c2t = 0.f;
;   if (MODE == 1) c2t = c2p[qpos];
;   const u64* mrow = P_mask + (size_t)(b * SEQ + qpos) * 64;
;   const int kch = ((tid & 15) ^ ((tid >> 4) & 7)) * 8;
;   const size_t ksrc = (size_t)(tid >> 4) * 128 + kch;
;   const int kk4 = ((tid >> 7) & 1) * 8 + ((tid & 31) >> 2);
;   const int vk = ((kk4 & ~0xC) | ((kk4 & 4) << 1) | ((kk4 & 8) >> 1)) + ((tid >> 8) & 1) * 16;
;   const size_t vsrc = (size_t)vk * 128 + ((tid >> 5) & 3) * 32 + (tid & 3) * 8;
;   f32x4 stc = {0.f, 0.f, 0.f, 0.f}; u64 mw = 0;
;     ...
;   LOADT(NT - 1, 0);
;   float m_reg = 0.f;
;   int started = 0;
;   f32x16 o[4], ol;
; #pragma unroll
;   for (int d = 0; d < 4; ++d) o[d] = f32x16{};
;   ol = f32x16{};
;   const bf16x8 ones = {0x3F80, 0x3F80, 0x3F80, 0x3F80, 0x3F80, 0x3F80, 0x3F80, 0x3F80};
;   const int vb_lane = (int)(uintptr_t)V_lds + v_rd_base(lane);
.LBB0_681:
	s_bitcmp0_b32 s55, 0
	s_cselect_b32 s9, s51, s52
	s_lshl_b32 s0, s55, 1
	s_add_i32 s33, s53, s0
	v_mov_b32_e32 v12, v184
	s_add_i32 s0, s33, s54
	s_ashr_i32 s1, s0, 31
	v_readfirstlane_b32 s10, v12
	s_and_b32 s34, s10, 0x3fffffc0
	s_lshl_b64 s[0:1], s[0:1], 20
	s_add_u32 s0, s80, s0
	s_addc_u32 s1, s81, s1
	s_ashr_i32 s10, s10, 1
	s_lshl_b32 s35, s9, 8
	s_and_b32 s36, s10, 0xffffffe0
	v_and_b32_e32 v169, 31, v12
	s_add_i32 s56, s36, s35
	s_ashr_i32 s6, s33, 3
	v_or_b32_e32 v2, s56, v169
	s_add_i32 s6, s6, s50
	v_ashrrev_i32_e32 v3, 31, v2
	s_ashr_i32 s7, s6, 31
	v_lshlrev_b64 v[4:5], 8, v[2:3]
	s_lshl_b32 s57, s9, 2
	v_lshl_add_u64 v[4:5], s[0:1], 0, v[4:5]
	s_lshl_b64 s[10:11], s[6:7], 20
	v_readlane_b32 s0, v250, 32
	v_bfe_u32 v13, v12, 5, 1
	s_add_u32 s0, s0, s10
	v_readlane_b32 s1, v250, 33
	v_lshrrev_b32_e32 v7, 5, v12
	v_lshlrev_b32_e32 v0, 4, v13
	s_addc_u32 s1, s1, s11
	v_and_b32_e32 v8, 4, v7
	v_lshrrev_b32_e32 v7, 1, v12
	v_lshl_add_u64 v[4:5], v[4:5], 0, v[0:1]
	s_add_u32 s6, s86, s10
	v_and_b32_e32 v10, 8, v7
	v_lshrrev_b32_e32 v11, 4, v12
	global_load_dwordx4 v[156:159], v[4:5], off
	global_load_dwordx4 v[152:155], v[4:5], off offset:32
	global_load_dwordx4 v[148:151], v[4:5], off offset:64
	global_load_dwordx4 v[144:147], v[4:5], off offset:96
	global_load_dwordx4 v[140:143], v[4:5], off offset:128
	global_load_dwordx4 v[136:139], v[4:5], off offset:160
	global_load_dwordx4 v[132:135], v[4:5], off offset:192
	global_load_dwordx4 v[128:131], v[4:5], off offset:224
	s_addc_u32 s7, s87, s11
	v_and_b32_e32 v5, 15, v12
	v_ashrrev_i32_e32 v4, 4, v12
	v_bfe_u32 v9, v12, 2, 2
	s_or_b32 s58, s57, 3
	v_and_or_b32 v10, v11, 16, v10
	v_bitop3_b32 v6, v4, v5, 7 bitop3:0x6c
	v_ashrrev_i32_e32 v5, 31, v4
	v_lshlrev_b32_e32 v15, 3, v12
	s_lshl_b32 s16, s58, 14
	v_or3_b32 v8, v8, v9, v10
	v_and_b32_e32 v14, 0x60, v12
	v_and_b32_e32 v16, 24, v15
	s_add_u32 s0, s0, s16
	v_lshlrev_b64 v[4:5], 8, v[4:5]
	v_lshlrev_b32_e32 v17, 4, v6
	v_lshlrev_b32_e32 v8, 7, v8
	s_addc_u32 s1, s1, 0
	v_or_b32_e32 v6, v4, v17
	v_mov_b32_e32 v7, v5
	v_or3_b32 v8, v8, v14, v16
	v_lshlrev_b32_e32 v14, 4, v12
	v_lshl_add_u64 v[6:7], s[0:1], 0, v[6:7]
	s_add_u32 s0, s6, s16
	v_add_u32_e32 v180, 16, v14
	s_addc_u32 s1, s7, 0
	v_lshlrev_b32_e32 v8, 1, v8
	v_mov_b32_e32 v9, v1
	v_add_u32_e32 v16, 0x8000, v180
	v_lshl_add_u64 v[10:11], s[0:1], 0, v[8:9]
	v_readfirstlane_b32 s0, v16
	s_mov_b32 m0, s0
	v_readfirstlane_b32 s0, v180
	v_add_u32_e32 v16, 0xa000, v180
	global_load_lds_dwordx4 v[6:7], off
	s_mov_b32 m0, s0
	v_readfirstlane_b32 s0, v16
	global_load_lds_dwordx4 v[10:11], off
	v_lshl_add_u64 v[6:7], v[6:7], 0, s[18:19]
	s_mov_b32 m0, s0
	v_add_u32_e32 v2, s49, v2
	global_load_lds_dwordx4 v[6:7], off
	v_lshl_add_u64 v[6:7], v[10:11], 0, s[18:19]
	v_add_u32_e32 v10, 0x2000, v180
	v_ashrrev_i32_e32 v3, 31, v2
	v_readfirstlane_b32 s0, v10
	s_mov_b32 m0, s0
	v_readlane_b32 s0, v250, 42
	v_lshlrev_b64 v[2:3], 9, v[2:3]
	v_readlane_b32 s1, v250, 43
	s_lshl_b32 s16, s9, 5
	global_load_lds_dwordx4 v[6:7], off
	v_lshl_add_u64 v[2:3], s[0:1], 0, v[2:3]
	v_lshl_add_u64 v[2:3], v[2:3], 0, s[16:17]
	global_load_dwordx2 v[166:167], v[2:3], off offset:24
	s_lshl_b32 s0, s34, 2
	s_add_i32 s0, s0, 16
	s_add_i32 s0, s0, 0x10200
	v_lshlrev_b32_e32 v6, 1, v12
	s_or_b32 s60, s56, 31
	v_and_b32_e32 v6, 32, v6
	s_cmp_lg_u32 16, -1
	v_and_b32_e32 v3, 0xc0, v14
	v_and_or_b32 v6, v15, s40, v6
	v_lshl_add_u32 v173, v169, 2, s0
	v_add_u32_e32 v172, s0, v0
	s_cselect_b32 s0, 16, 0
	v_add3_u32 v171, v3, s0, v6
	s_add_i32 s0, s49, s35
	v_and_b32_e32 v2, 63, v12
	s_add_i32 s0, s0, s36
	v_cmp_gt_u32_e64 s[6:7], 32, v2
	v_add_u32_e32 v2, s0, v169
	v_ashrrev_i32_e32 v3, 31, v2
	s_lshl_b32 s0, s9, 16
	v_lshlrev_b64 v[2:3], 9, v[2:3]
	s_or_b32 s10, s10, s0
	v_and_b32_e32 v7, 0x70, v14
	v_bitop3_b32 v183, v0, v14, s41 bitop3:0x78
	v_or_b32_e32 v2, s16, v2
	s_waitcnt vmcnt(0)
	v_lshl_add_u64 v[162:163], s[10:11], 0, v[4:5]
	v_mov_b32_e32 v14, v1
	v_mov_b32_e32 v15, v1
	v_lshlrev_b32_e32 v170, 2, v13
	v_bitop3_b32 v181, v0, v7, 32 bitop3:0x36
	v_bitop3_b32 v179, v0, v7, 64 bitop3:0x36
	v_bitop3_b32 v178, v0, v7, s2 bitop3:0x36
	v_bitop3_b32 v177, v0, v7, s42 bitop3:0x36
	v_bitop3_b32 v176, v0, v7, s43 bitop3:0x36
	v_bitop3_b32 v175, v0, v7, s3 bitop3:0x36
	v_bitop3_b32 v174, v0, v7, s44 bitop3:0x36
	v_lshl_add_u64 v[160:161], v[2:3], 0, s[20:21]
	v_or_b32_e32 v162, v162, v17
	v_lshl_add_u64 v[164:165], s[10:11], 0, v[8:9]
	v_mov_b32_e32 v0, v1
	v_mov_b32_e32 v2, v1
	v_mov_b32_e32 v3, v1
	v_mov_b32_e32 v4, v1
	v_mov_b32_e32 v5, v1
	v_mov_b32_e32 v6, v1
	v_mov_b32_e32 v7, v1
	v_mov_b32_e32 v8, v1
	v_mov_b32_e32 v10, v1
	v_mov_b32_e32 v11, v1
	v_mov_b32_e32 v12, v1
	v_mov_b32_e32 v13, v1
	v_mov_b64_e32 v[30:31], v[14:15]
	v_mov_b64_e32 v[46:47], v[14:15]
	v_mov_b64_e32 v[62:63], v[14:15]
	v_mov_b64_e32 v[78:79], v[14:15]
	v_mov_b64_e32 v[94:95], v[14:15]
	s_mov_b32 s59, 0
	v_lshl_add_u32 v182, v169, 8, 16
	s_or_b32 s16, s35, 0xc0
	v_mov_b32_e32 v186, 0
	v_mov_b64_e32 v[28:29], v[12:13]
	v_mov_b64_e32 v[26:27], v[10:11]
	v_mov_b64_e32 v[24:25], v[8:9]
	v_mov_b64_e32 v[22:23], v[6:7]
	v_mov_b64_e32 v[20:21], v[4:5]
	v_mov_b64_e32 v[18:19], v[2:3]
	v_mov_b64_e32 v[16:17], v[0:1]
	v_mov_b64_e32 v[44:45], v[12:13]
	v_mov_b64_e32 v[42:43], v[10:11]
	v_mov_b64_e32 v[40:41], v[8:9]
	v_mov_b64_e32 v[38:39], v[6:7]
	v_mov_b64_e32 v[36:37], v[4:5]
	v_mov_b64_e32 v[34:35], v[2:3]
	v_mov_b64_e32 v[32:33], v[0:1]
	v_mov_b64_e32 v[60:61], v[12:13]
	v_mov_b64_e32 v[58:59], v[10:11]
	v_mov_b64_e32 v[56:57], v[8:9]
	v_mov_b64_e32 v[54:55], v[6:7]
	v_mov_b64_e32 v[52:53], v[4:5]
	v_mov_b64_e32 v[50:51], v[2:3]
	v_mov_b64_e32 v[48:49], v[0:1]
	v_mov_b64_e32 v[76:77], v[12:13]
	v_mov_b64_e32 v[74:75], v[10:11]
	v_mov_b64_e32 v[72:73], v[8:9]
	v_mov_b64_e32 v[70:71], v[6:7]
	v_mov_b64_e32 v[68:69], v[4:5]
	v_mov_b64_e32 v[66:67], v[2:3]
	v_mov_b64_e32 v[64:65], v[0:1]
	s_mov_b32 s0, 0
	v_mov_b64_e32 v[92:93], v[12:13]
	v_mov_b64_e32 v[90:91], v[10:11]
	v_mov_b64_e32 v[88:89], v[8:9]
	v_mov_b64_e32 v[86:87], v[6:7]
	v_mov_b64_e32 v[84:85], v[4:5]
	v_mov_b64_e32 v[82:83], v[2:3]
	v_mov_b64_e32 v[80:81], v[0:1]
	v_lshl_add_u64 v[162:163], v[162:163], 0, s[94:95]
	v_lshl_add_u64 v[164:165], v[164:165], 0, s[94:95]
	v_lshl_add_u64 v[160:161], v[160:161], 0, s[94:95]
	v_lshl_add_u64 v[248:249], v[162:163], 0, s[26:27]
	v_lshl_add_u64 v[252:253], v[164:165], 0, s[28:29]
	v_lshl_add_u64 v[162:163], v[162:163], 0, s[22:23]
	v_lshl_add_u64 v[164:165], v[164:165], 0, s[24:25]
	v_readfirstlane_b32 s99, v180
	.p2align	6
